# decode attention item: q.k dot loop and p.v loop read LDS 8/16 elements ahead with counted lgkmcnt waits (same summation order)
# speedup vs baseline: 1.0135x; 1.0135x over previous
; DI float shx(float v, int m, int lane) { return __int_as_float(__builtin_amdgcn_ds_bpermute((lane ^ m) << 2, __float_as_int(v))); }
; DI void att_sample_item(char* shm, const Params& P, int l, int s) {
;     ...
;     const int g = tid >> 7, c = 1 + (tid & 127), qh = kvh * 4 + g;
;     float dot = 0.f;
;     _Pragma("unroll 1") for (int d = 0; d < 64; ++d) dot += qv[g * 64 + d] * Kc[c * 65 + d];
;     const float score = dot * 0.125f + bt[(128 - c) * 16 + qh];
;     float mx = score;
;     for (int o = 32; o >= 1; o >>= 1) mx = fmaxf(mx, shx(mx, o, lane));
;     if (lane == 0) red[w] = mx;
.LBB0_122:
	v_add_u32_e32 v0, s22, v85
	v_add_u32_e32 v1, s22, v84
	ds_read2_b32 v[92:93], v0 offset1:1
	ds_read2_b32 v[100:101], v1 offset1:1
	ds_read2_b32 v[94:95], v0 offset0:2 offset1:3
	ds_read2_b32 v[102:103], v1 offset0:2 offset1:3
	ds_read2_b32 v[96:97], v0 offset0:4 offset1:5
	ds_read2_b32 v[104:105], v1 offset0:4 offset1:5
	ds_read2_b32 v[98:99], v0 offset0:6 offset1:7
	ds_read2_b32 v[106:107], v1 offset0:6 offset1:7
	s_add_i32 s22, s22, 32
	s_cmpk_eq_i32 s22, 0x100
	s_waitcnt lgkmcnt(6)
	v_fmac_f32_e32 v2, v92, v100
	v_fmac_f32_e32 v2, v93, v101
	s_waitcnt lgkmcnt(4)
	v_fmac_f32_e32 v2, v94, v102
	v_fmac_f32_e32 v2, v95, v103
	s_waitcnt lgkmcnt(2)
	v_fmac_f32_e32 v2, v96, v104
	v_fmac_f32_e32 v2, v97, v105
	s_waitcnt lgkmcnt(0)
	v_fmac_f32_e32 v2, v98, v106
	v_fmac_f32_e32 v2, v99, v107
	s_cbranch_scc0 .LBB0_122
	s_lshl_b32 s25, s24, 2
	v_add_u32_e32 v1, s25, v63
	v_add_u32_e32 v4, v1, v66
	v_ashrrev_i32_e32 v5, 31, v4
	v_lshl_add_u64 v[4:5], v[4:5], 2, s[16:17]
	global_load_dword v0, v[4:5], off offset:256
	s_waitcnt vmcnt(0)
	v_fmac_f32_e32 v0, 0x3e000000, v2
	ds_bpermute_b32 v2, v78, v0
	s_waitcnt lgkmcnt(0)
	v_max_f32_e32 v2, v2, v2
	v_max_f32_e32 v2, v0, v2
	ds_bpermute_b32 v3, v79, v2
	s_waitcnt lgkmcnt(0)
	v_max_f32_e32 v3, v3, v3
	v_max_f32_e32 v2, v2, v3
	ds_bpermute_b32 v3, v80, v2
	s_waitcnt lgkmcnt(0)
	v_max_f32_e32 v3, v3, v3
	v_max_f32_e32 v2, v2, v3
	ds_bpermute_b32 v3, v81, v2
	s_waitcnt lgkmcnt(0)
	v_max_f32_e32 v3, v3, v3
	v_max_f32_e32 v2, v2, v3
	ds_bpermute_b32 v3, v82, v2
	s_waitcnt lgkmcnt(0)
	v_max_f32_e32 v3, v3, v3
	v_max_f32_e32 v2, v2, v3
	ds_bpermute_b32 v3, v83, v2
	s_and_saveexec_b64 s[22:23], s[6:7]
	s_cbranch_execz .LBB0_125
	s_waitcnt lgkmcnt(0)
	v_max_f32_e32 v3, v3, v3
	v_max_f32_e32 v2, v2, v2
	v_max_f32_e32 v2, v2, v3
	ds_write_b32 v75, v2

; DI u16 f2bf(float x) { return (u16)(pack2(x, 0.f) & 0xffffu); }
; DI void att_sample_item(char* shm, const Params& P, int l, int s) {
;     ...
;     if (tid < 256) {
;       const int g2 = tid >> 6, d = tid & 63; float o = 0.f;
;       for (int cc = 1; cc <= 128; ++cc) o += sc[g2 * 128 + cc - 1] * Vc[cc * 65 + d];
;       zr[C_AQ + (kvh * 4 + g2) * 64 + d] = f2bf(o);
;     }
.LBB0_129:
	v_add_u32_e32 v3, 16, v1
	v_add_u32_e32 v4, 0x10a08, v3
	v_add_u32_e32 v8, 16, v2
	v_add_u32_e32 v9, 0x400, v8
	v_add_u32_e32 v5, 0x800, v8
	v_add_u32_e32 v6, 0xc00, v8
	ds_read2_b32 v[108:109], v4 offset1:1
	ds_read2_b32 v[110:111], v8 offset1:65
	ds_read2_b32 v[112:113], v4 offset0:2 offset1:3
	ds_read2_b32 v[114:115], v8 offset0:130 offset1:195
	ds_read2_b32 v[116:117], v4 offset0:4 offset1:5
	ds_read2_b32 v[118:119], v9 offset0:4 offset1:69
	ds_read2_b32 v[120:121], v4 offset0:6 offset1:7
	ds_read2_b32 v[122:123], v9 offset0:134 offset1:199
	ds_read2_b32 v[124:125], v4 offset0:8 offset1:9
	ds_read2_b32 v[126:127], v5 offset0:8 offset1:73
	ds_read2_b32 v[128:129], v4 offset0:10 offset1:11
	ds_read2_b32 v[130:131], v5 offset0:138 offset1:203
	ds_read2_b32 v[132:133], v4 offset0:12 offset1:13
	ds_read2_b32 v[134:135], v6 offset0:12 offset1:77
	ds_read2_b32 v[136:137], v4 offset0:14 offset1:15
	ds_read2_b32 v[138:139], v6 offset0:142 offset1:207
	s_add_i32 s26, s26, -16
	v_add_u32_e32 v2, 0x1040, v2
	v_add_u32_e32 v1, 64, v1
	s_cmp_eq_u32 s26, 0
	s_waitcnt lgkmcnt(14)
	v_fmac_f32_e32 v0, v108, v110
	v_fmac_f32_e32 v0, v109, v111
	s_waitcnt lgkmcnt(12)
	v_fmac_f32_e32 v0, v112, v114
	v_fmac_f32_e32 v0, v113, v115
	s_waitcnt lgkmcnt(10)
	v_fmac_f32_e32 v0, v116, v118
	v_fmac_f32_e32 v0, v117, v119
	s_waitcnt lgkmcnt(8)
	v_fmac_f32_e32 v0, v120, v122
	v_fmac_f32_e32 v0, v121, v123
	s_waitcnt lgkmcnt(6)
	v_fmac_f32_e32 v0, v124, v126
	v_fmac_f32_e32 v0, v125, v127
	s_waitcnt lgkmcnt(4)
	v_fmac_f32_e32 v0, v128, v130
	v_fmac_f32_e32 v0, v129, v131
	s_waitcnt lgkmcnt(2)
	v_fmac_f32_e32 v0, v132, v134
	v_fmac_f32_e32 v0, v133, v135
	s_waitcnt lgkmcnt(0)
	v_fmac_f32_e32 v0, v136, v138
	v_fmac_f32_e32 v0, v137, v139
	s_cbranch_scc0 .LBB0_129
	v_cvt_pk_bf16_f32 v2, v0, s0
	v_add_u32_e32 v0, s25, v62
	v_lshl_or_b32 v0, v0, 6, v61
	v_ashrrev_i32_e32 v1, 31, v0
	v_lshl_add_u64 v[0:1], v[0:1], 1, s[0:1]
	global_store_short v[0:1], v2, off
	s_branch .LBB0_110
